# adds pipelined LDS read-modify-write in diff-unit epilogue (8 reads in flight) on top of v56
# speedup vs baseline: 1.0193x; 1.0038x over previous
; __device__ __forceinline__ int crow(int r, int hi) { return (r & 3) + 8 * (r >> 2) + 4 * hi; }
; __device__ __forceinline__ void diff_unit(const DiffArgs& A, int b, int h, int qb, char* lds, int wv) {
;     ...
;     if (c == 0) {
; #pragma unroll
;         for (int r = 0; r < 16; ++r) { float* orow = OS + (wq * 32 + crow(r, hi)) * 132 + r32;
; #pragma unroll
;             for (int d0 = 0; d0 < 4; ++d0) orow[d0 * 32] = o[d0][r] * rli[r] - orow[d0 * 32]; }
;     }
.LBB0_267:
	s_andn2_b64 vcc, exec, s[36:37]
	s_waitcnt lgkmcnt(0)
	s_barrier
	s_cbranch_vccnz .LBB0_269
	v_lshl_or_b32 v67, v78, 2, s23
	s_movk_i32 s0, 0x210
	v_mul_lo_u32 v67, v67, s0
	v_add3_u32 v66, 0, v66, v67
	v_add_u32_e32 v166, 0x0, v66
	ds_read2_b32 v[150:151], v166 offset0:0 offset1:32
	v_add_u32_e32 v167, 0x0, v66
	ds_read2_b32 v[152:153], v167 offset0:64 offset1:96
	v_add_u32_e32 v168, 0x0, v66
	ds_read2_b32 v[154:155], v168 offset0:132 offset1:164
	v_add_u32_e32 v169, 0x0, v66
	ds_read2_b32 v[156:157], v169 offset0:196 offset1:228
	v_add_u32_e32 v170, 0x400, v66
	ds_read2_b32 v[158:159], v170 offset0:8 offset1:40
	v_add_u32_e32 v171, 0x400, v66
	ds_read2_b32 v[160:161], v171 offset0:72 offset1:104
	v_add_u32_e32 v172, 0x400, v66
	ds_read2_b32 v[162:163], v172 offset0:140 offset1:172
	v_add_u32_e32 v173, 0x400, v66
	ds_read2_b32 v[164:165], v173 offset0:204 offset1:236
	s_waitcnt lgkmcnt(7)
	v_fma_f32 v150, v48, v81, -v150
	v_fma_f32 v151, v32, v81, -v151
	ds_write2_b32 v166, v150, v151 offset0:0 offset1:32
	s_waitcnt lgkmcnt(7)
	v_fma_f32 v152, v16, v81, -v152
	v_fma_f32 v153, v0, v81, -v153
	ds_write2_b32 v167, v152, v153 offset0:64 offset1:96
	s_waitcnt lgkmcnt(7)
	v_fma_f32 v154, v49, v80, -v154
	v_fma_f32 v155, v33, v80, -v155
	ds_write2_b32 v168, v154, v155 offset0:132 offset1:164
	s_waitcnt lgkmcnt(7)
	v_fma_f32 v156, v17, v80, -v156
	v_fma_f32 v157, v1, v80, -v157
	ds_write2_b32 v169, v156, v157 offset0:196 offset1:228
	s_waitcnt lgkmcnt(7)
	v_fma_f32 v158, v50, v79, -v158
	v_fma_f32 v159, v34, v79, -v159
	ds_write2_b32 v170, v158, v159 offset0:8 offset1:40
	s_waitcnt lgkmcnt(7)
	v_fma_f32 v160, v18, v79, -v160
	v_fma_f32 v161, v2, v79, -v161
	ds_write2_b32 v171, v160, v161 offset0:72 offset1:104
	s_waitcnt lgkmcnt(7)
	v_fma_f32 v162, v51, v77, -v162
	v_fma_f32 v163, v35, v77, -v163
	ds_write2_b32 v172, v162, v163 offset0:140 offset1:172
	s_waitcnt lgkmcnt(7)
	v_fma_f32 v164, v19, v77, -v164
	v_fma_f32 v165, v3, v77, -v165
	ds_write2_b32 v173, v164, v165 offset0:204 offset1:236
	v_add_u32_e32 v166, 0x1000, v66
	ds_read2_b32 v[150:151], v166 offset0:32 offset1:64
	v_add_u32_e32 v167, 0x1000, v66
	ds_read2_b32 v[152:153], v167 offset0:96 offset1:128
	v_add_u32_e32 v168, 0x1000, v66
	ds_read2_b32 v[154:155], v168 offset0:164 offset1:196
	v_add_u32_e32 v169, 0x1200, v66
	ds_read2_b32 v[156:157], v169 offset0:100 offset1:132
	v_add_u32_e32 v170, 0x1400, v66
	ds_read2_b32 v[158:159], v170 offset0:40 offset1:72
	v_add_u32_e32 v171, 0x1400, v66
	ds_read2_b32 v[160:161], v171 offset0:104 offset1:136
	v_add_u32_e32 v172, 0x1400, v66
	ds_read2_b32 v[162:163], v172 offset0:172 offset1:204
	v_add_u32_e32 v173, 0x1600, v66
	ds_read2_b32 v[164:165], v173 offset0:108 offset1:140
	s_waitcnt lgkmcnt(7)
	v_fma_f32 v150, v52, v76, -v150
	v_fma_f32 v151, v36, v76, -v151
	ds_write2_b32 v166, v150, v151 offset0:32 offset1:64
	s_waitcnt lgkmcnt(7)
	v_fma_f32 v152, v20, v76, -v152
	v_fma_f32 v153, v4, v76, -v153
	ds_write2_b32 v167, v152, v153 offset0:96 offset1:128
	s_waitcnt lgkmcnt(7)
	v_fma_f32 v154, v53, v75, -v154
	v_fma_f32 v155, v37, v75, -v155
	ds_write2_b32 v168, v154, v155 offset0:164 offset1:196
	s_waitcnt lgkmcnt(7)
	v_fma_f32 v156, v21, v75, -v156
	v_fma_f32 v157, v5, v75, -v157
	ds_write2_b32 v169, v156, v157 offset0:100 offset1:132
	s_waitcnt lgkmcnt(7)
	v_fma_f32 v158, v54, v74, -v158
	v_fma_f32 v159, v38, v74, -v159
	ds_write2_b32 v170, v158, v159 offset0:40 offset1:72
	s_waitcnt lgkmcnt(7)
	v_fma_f32 v160, v22, v74, -v160
	v_fma_f32 v161, v6, v74, -v161
	ds_write2_b32 v171, v160, v161 offset0:104 offset1:136
	s_waitcnt lgkmcnt(7)
	v_fma_f32 v162, v55, v73, -v162
	v_fma_f32 v163, v39, v73, -v163
	ds_write2_b32 v172, v162, v163 offset0:172 offset1:204
	s_waitcnt lgkmcnt(7)
; __device__ __forceinline__ int crow(int r, int hi) { return (r & 3) + 8 * (r >> 2) + 4 * hi; }
; __device__ __forceinline__ void diff_unit(const DiffArgs& A, int b, int h, int qb, char* lds, int wv) {
;     ...
;     if (c == 0) {
; #pragma unroll
;         for (int r = 0; r < 16; ++r) { float* orow = OS + (wq * 32 + crow(r, hi)) * 132 + r32;
; #pragma unroll
;             for (int d0 = 0; d0 < 4; ++d0) orow[d0 * 32] = o[d0][r] * rli[r] - orow[d0 * 32]; }
;     }
	v_fma_f32 v164, v23, v73, -v164
	v_fma_f32 v165, v7, v73, -v165
	ds_write2_b32 v173, v164, v165 offset0:108 offset1:140
	v_add_u32_e32 v166, 0x2000, v66
	ds_read2_b32 v[150:151], v166 offset0:64 offset1:96
	v_add_u32_e32 v167, 0x2000, v66
	ds_read2_b32 v[152:153], v167 offset0:128 offset1:160
	v_add_u32_e32 v168, 0x2000, v66
	ds_read2_b32 v[154:155], v168 offset0:196 offset1:228
	v_add_u32_e32 v169, 0x2400, v66
	ds_read2_b32 v[156:157], v169 offset0:4 offset1:36
	v_add_u32_e32 v170, 0x2400, v66
	ds_read2_b32 v[158:159], v170 offset0:72 offset1:104
	v_add_u32_e32 v171, 0x2400, v66
	ds_read2_b32 v[160:161], v171 offset0:136 offset1:168
	v_add_u32_e32 v172, 0x2400, v66
	ds_read2_b32 v[162:163], v172 offset0:204 offset1:236
	v_add_u32_e32 v173, 0x2800, v66
	ds_read2_b32 v[164:165], v173 offset0:12 offset1:44
	s_waitcnt lgkmcnt(7)
	v_fma_f32 v150, v56, v72, -v150
	v_fma_f32 v151, v40, v72, -v151
	ds_write2_b32 v166, v150, v151 offset0:64 offset1:96
	s_waitcnt lgkmcnt(7)
	v_fma_f32 v152, v24, v72, -v152
	v_fma_f32 v153, v8, v72, -v153
	ds_write2_b32 v167, v152, v153 offset0:128 offset1:160
	s_waitcnt lgkmcnt(7)
	v_fma_f32 v154, v57, v71, -v154
	v_fma_f32 v155, v41, v71, -v155
	ds_write2_b32 v168, v154, v155 offset0:196 offset1:228
	s_waitcnt lgkmcnt(7)
	v_fma_f32 v156, v25, v71, -v156
	v_fma_f32 v157, v9, v71, -v157
	ds_write2_b32 v169, v156, v157 offset0:4 offset1:36
	s_waitcnt lgkmcnt(7)
	v_fma_f32 v158, v58, v70, -v158
	v_fma_f32 v159, v42, v70, -v159
	ds_write2_b32 v170, v158, v159 offset0:72 offset1:104
	s_waitcnt lgkmcnt(7)
	v_fma_f32 v160, v26, v70, -v160
	v_fma_f32 v161, v10, v70, -v161
	ds_write2_b32 v171, v160, v161 offset0:136 offset1:168
	s_waitcnt lgkmcnt(7)
	v_fma_f32 v162, v59, v69, -v162
	v_fma_f32 v163, v43, v69, -v163
	ds_write2_b32 v172, v162, v163 offset0:204 offset1:236
	s_waitcnt lgkmcnt(7)
	v_fma_f32 v164, v27, v69, -v164
	v_fma_f32 v165, v11, v69, -v165
	ds_write2_b32 v173, v164, v165 offset0:12 offset1:44
	v_add_u32_e32 v166, 0x3000, v66
	ds_read2_b32 v[150:151], v166 offset0:96 offset1:128
	v_add_u32_e32 v167, 0x3000, v66
	ds_read2_b32 v[152:153], v167 offset0:160 offset1:192
	v_add_u32_e32 v168, 0x3200, v66
	ds_read2_b32 v[154:155], v168 offset0:100 offset1:132
	v_add_u32_e32 v169, 0x3400, v66
	ds_read2_b32 v[156:157], v169 offset0:36 offset1:68
	v_add_u32_e32 v170, 0x3400, v66
	ds_read2_b32 v[158:159], v170 offset0:104 offset1:136
	v_add_u32_e32 v171, 0x3400, v66
	ds_read2_b32 v[160:161], v171 offset0:168 offset1:200
	v_add_u32_e32 v172, 0x3600, v66
	ds_read2_b32 v[162:163], v172 offset0:108 offset1:140
	v_add_u32_e32 v173, 0x3800, v66
	ds_read2_b32 v[164:165], v173 offset0:44 offset1:76
	s_waitcnt lgkmcnt(7)
	v_fma_f32 v150, v60, v82, -v150
	v_fma_f32 v151, v44, v82, -v151
	ds_write2_b32 v166, v150, v151 offset0:96 offset1:128
	s_waitcnt lgkmcnt(7)
	v_fma_f32 v152, v28, v82, -v152
	v_fma_f32 v153, v12, v82, -v153
	ds_write2_b32 v167, v152, v153 offset0:160 offset1:192
	s_waitcnt lgkmcnt(7)
	v_fma_f32 v154, v61, v83, -v154
	v_fma_f32 v155, v45, v83, -v155
	ds_write2_b32 v168, v154, v155 offset0:100 offset1:132
	s_waitcnt lgkmcnt(7)
	v_fma_f32 v156, v29, v83, -v156
	v_fma_f32 v157, v13, v83, -v157
	ds_write2_b32 v169, v156, v157 offset0:36 offset1:68
	s_waitcnt lgkmcnt(7)
	v_fma_f32 v158, v62, v65, -v158
	v_fma_f32 v159, v46, v65, -v159
	ds_write2_b32 v170, v158, v159 offset0:104 offset1:136
	s_waitcnt lgkmcnt(7)
	v_fma_f32 v160, v30, v65, -v160
	v_fma_f32 v161, v14, v65, -v161
	ds_write2_b32 v171, v160, v161 offset0:168 offset1:200
	s_waitcnt lgkmcnt(7)
	v_fma_f32 v162, v63, v64, -v162
	v_fma_f32 v163, v47, v64, -v163
	ds_write2_b32 v172, v162, v163 offset0:108 offset1:140
	s_waitcnt lgkmcnt(7)
	v_fma_f32 v164, v31, v64, -v164
	v_fma_f32 v165, v15, v64, -v165
	ds_write2_b32 v173, v164, v165 offset0:44 offset1:76
